# XCD-local grid barrier (no L2 writeback, no cross-XCD hop) on the three GEMM->GEMM seams whose rows are owned per XCD; runtime placement guard falls back to the full barrier
# speedup vs baseline: 1.0072x; 1.0011x over previous
; __device__ __forceinline__ int opaque_tid(int wv) { unsigned ones = ~0u; asm volatile("" : "+s"(ones)); int lane = __builtin_amdgcn_mbcnt_hi(ones, __builtin_amdgcn_mbcnt_lo(ones, 0u)); int t = (wv << 6) | lane; asm volatile("" : "+v"(t)); return t; }
; #define LAS __attribute__((address_space(3)))
; __device__ __forceinline__ unsigned xb_add(unsigned* p, unsigned v) { return __hip_atomic_fetch_add(p, v, __ATOMIC_RELAXED, __HIP_MEMORY_SCOPE_AGENT); }
; __device__ __forceinline__ unsigned xb_xcc_id() { return (unsigned)__builtin_amdgcn_s_getreg((3 << 11) | 20) & 0xFu; }
; #define BARRIER_WS ((unsigned*)(kargs_ptr()->ws + OFF_BAR))
; __device__ __forceinline__ XcdBarrier xcd_barrier_post(unsigned* bar, volatile LAS unsigned* st, bool t0) {
;     XcdBarrier b; b.bar = bar; b.x = xb_xcc_id(); b.st = st;
;     if (t0) (void)xb_add(&bar[XB_XCNT(b.x)], 1u);
;     return b;
; }
; __global__ void __launch_bounds__(512, 2) fwd_megakernel(KArgs ka_unused) {
;     ...
;   grid.sync();
;   {
;     volatile LAS unsigned* xb_st = (volatile LAS unsigned*)(shm + LDS_BYTES - 16);
;     if (opaque_tid(wv) == 0) { xb_st[0] = 0u; xb_st[1] = 0u; }
;     __syncthreads();
;     (void)xcd_barrier_post(BARRIER_WS, xb_st, opaque_tid(wv) == 0);
;   }
.LBB0_45:
	s_or_b64 exec, exec, s[2:3]
	s_mov_b32 s0, -1
	s_barrier
	s_mov_b32 s4, -1
	v_mbcnt_lo_u32_b32 v0, s0, 0
	v_mbcnt_hi_u32_b32 v0, s0, v0
	v_or_b32_e32 v0, s97, v0
	s_nop 0
	v_cmp_eq_u32_e32 vcc, 0, v0
	s_and_saveexec_b64 s[0:1], vcc
	s_cbranch_execz .LBB0_47
	s_add_i32 s2, 0, 0x23ff0
	v_mov_b32_e32 v0, 0
	v_mov_b32_e32 v1, s2
	s_add_i32 s2, 0, 0x23ff4
	ds_write_b32 v1, v0
	v_mov_b32_e32 v1, s2
	ds_write_b32 v1, v0
	s_add_i32 s2, 0, 0x23ff8
	v_mov_b32_e32 v1, s2
	ds_write_b32 v1, v0
.LBB0_47:
	s_or_b64 exec, exec, s[0:1]
	s_mov_b64 s[2:3], s[54:55]
	s_waitcnt lgkmcnt(0)
	s_barrier
	s_nop 0
	v_mbcnt_lo_u32_b32 v0, s4, 0
	v_mbcnt_hi_u32_b32 v0, s4, v0
	v_or_b32_e32 v0, s97, v0
	s_getreg_b32 s6, hwreg(HW_REG_XCC_ID, 0, 4)
	v_cmp_eq_u32_e32 vcc, 0, v0
	s_and_saveexec_b64 s[0:1], vcc
	s_cbranch_execz .LBB0_50
	s_mov_b64 s[4:5], exec
	v_mbcnt_lo_u32_b32 v0, s4, 0
	v_mbcnt_hi_u32_b32 v0, s5, v0
	v_cmp_eq_u32_e32 vcc, 0, v0
	s_and_b64 s[8:9], exec, vcc
	s_mov_b64 exec, s[8:9]
	s_cbranch_execz .LBB0_50
	s_load_dwordx2 s[2:3], s[2:3], 0x80
	s_lshl_b32 s6, s6, 8
	s_and_b32 s6, s6, 0xf00
	v_mov_b32_e32 v0, 0x1fa02000
	s_waitcnt lgkmcnt(0)
	s_add_u32 s2, s2, s6
	s_addc_u32 s3, s3, 0
	s_bcnt1_i32_b64 s4, s[4:5]
	v_mov_b32_e32 v1, s4
	global_atomic_add v0, v1, s[2:3] offset:1024
	s_sub_u32 s2, s2, s6
	s_subb_u32 s3, s3, 0
	s_lshr_b32 s6, s6, 8
	s_and_b32 s4, s72, 7
	s_lshl_b32 s4, s4, 3
	s_add_u32 s2, s2, s4
	s_addc_u32 s3, s3, 0
	v_mov_b32_e32 v1, s6
	global_atomic_add v0, v1, s[2:3]
	s_mul_i32 s6, s6, s6
	v_mov_b32_e32 v1, s6
	global_atomic_add v0, v1, s[2:3] offset:4

; __device__ __forceinline__ unsigned xb_ld(unsigned* p)              { return __hip_atomic_load(p, __ATOMIC_RELAXED, __HIP_MEMORY_SCOPE_AGENT); }
; __device__ __forceinline__ unsigned xb_add(unsigned* p, unsigned v) { return __hip_atomic_fetch_add(p, v, __ATOMIC_RELAXED, __HIP_MEMORY_SCOPE_AGENT); }
; #define XB_SPIN(cond, bar) do { unsigned _sp = 0; while (cond) { __builtin_amdgcn_s_sleep(1); \
;     if ((++_sp & 255u) == 0u) { if (xb_ld(&(bar)[XB_TMO])) break; if (_sp > XB_SPIN_CAP) { atomicAdd(&(bar)[XB_TMO], 1u); break; } } } } while (0)
; __device__ __forceinline__ void xcd_barrier(const XcdBarrier& b, bool t0) {
;     asm volatile("s_waitcnt vmcnt(0)" ::: "memory");
;     __syncthreads();
;     if (t0) {
;         unsigned* bar = b.bar;
;         __builtin_amdgcn_s_waitcnt(0);
;         unsigned nloc = b.st[0], nx = b.st[1];
;         if (nloc == 0u) { xcd_barrier_complete(bar, b.x, nloc, nx); b.st[0] = nloc; b.st[1] = nx; }
;         const unsigned old = xb_add(&bar[XB_XSUB(b.x)], 1u);
;         const unsigned gen = old / nloc;
;         if (old + 1u == (gen + 1u) * nloc) {
;             __builtin_amdgcn_fence(__ATOMIC_RELEASE, "agent");
;             asm volatile("s_waitcnt vmcnt(0)" ::: "memory");
;             const unsigned og = xb_add(&bar[XB_TOP], 1u);
;             const unsigned tg = og / nx;
;             if (og + 1u == (tg + 1u) * nx) xb_add(&bar[XB_TOPGEN], 1u);
;             else XB_SPIN(xb_ld(&bar[XB_TOPGEN]) == tg, bar);
;             __builtin_amdgcn_fence(__ATOMIC_ACQUIRE, "agent");
;             xb_add(&bar[XB_XGEN(b.x)], 1u);
;             asm volatile("s_waitcnt vmcnt(0)" ::: "memory");
;         } else {
;             XB_SPIN(xb_ld(&bar[XB_XGEN(b.x)]) == gen, bar);
;             __builtin_amdgcn_fence(__ATOMIC_ACQUIRE, "agent");
;             asm volatile("s_waitcnt vmcnt(0)" ::: "memory");
;         }
;     }
;     __syncthreads();
; }
.LBB0_1943:
	s_waitcnt lgkmcnt(0)
	s_mov_b64 s[6:7], s[54:55]
	s_mov_b32 s0, -1
	s_getreg_b32 s8, hwreg(HW_REG_XCC_ID, 0, 4)
	s_nop 0
	v_mbcnt_lo_u32_b32 v0, s0, 0
	v_mbcnt_hi_u32_b32 v0, s0, v0
	v_or_b32_e32 v0, s97, v0
	s_waitcnt vmcnt(0)
	s_nop 0
	v_cmp_eq_u32_e32 vcc, 0, v0
	s_barrier
	s_and_saveexec_b64 s[0:1], vcc
	s_cbranch_execz .LBB0_1995
	v_readlane_b32 s9, v254, 32
	s_load_dwordx2 s[10:11], s[54:55], 0x80
	v_mov_b32_e32 v0, s9
	ds_read_b32 v2, v0
	ds_read_b32 v3, v0 offset:8
	s_waitcnt lgkmcnt(0)
	v_readfirstlane_b32 s12, v3
	v_readfirstlane_b32 s13, v2
	s_cmp_eq_u32 s12, 2
	s_cbranch_scc1 .Lxl0_full
	s_cmp_eq_u32 s13, 0
	s_cbranch_scc1 .Lxl0_full
	s_cmp_eq_u32 s12, 1
	s_cbranch_scc1 .Lxl0_go
	v_mov_b32_e32 v4, 0x1fa02000
	global_load_dwordx4 v[8:11], v4, s[10:11] sc1
	global_load_dwordx4 v[12:15], v4, s[10:11] offset:16 sc1
	global_load_dwordx4 v[16:19], v4, s[10:11] offset:32 sc1
	global_load_dwordx4 v[20:23], v4, s[10:11] offset:48 sc1
	s_lshr_b32 s16, s70, 3
	s_and_b32 s17, s70, 7
	v_mov_b32_e32 v5, s17
	s_waitcnt vmcnt(0)
	v_mul_lo_u32 v6, v8, v8
	v_mul_lo_u32 v7, v9, s16
	v_sub_u32_e32 v6, v7, v6
	v_or_b32_e32 v5, v5, v6
	v_mul_lo_u32 v6, v10, v10
	v_mul_lo_u32 v7, v11, s16
	v_sub_u32_e32 v6, v7, v6
	v_or_b32_e32 v5, v5, v6
	v_mul_lo_u32 v6, v12, v12
	v_mul_lo_u32 v7, v13, s16
	v_sub_u32_e32 v6, v7, v6
	v_or_b32_e32 v5, v5, v6
	v_mul_lo_u32 v6, v14, v14
	v_mul_lo_u32 v7, v15, s16
	v_sub_u32_e32 v6, v7, v6
	v_or_b32_e32 v5, v5, v6
	v_mul_lo_u32 v6, v16, v16
	v_mul_lo_u32 v7, v17, s16
	v_sub_u32_e32 v6, v7, v6
	v_or_b32_e32 v5, v5, v6
	v_mul_lo_u32 v6, v18, v18
	v_mul_lo_u32 v7, v19, s16
	v_sub_u32_e32 v6, v7, v6
	v_or_b32_e32 v5, v5, v6
	v_mul_lo_u32 v6, v20, v20
	v_mul_lo_u32 v7, v21, s16
	v_sub_u32_e32 v6, v7, v6
	v_or_b32_e32 v5, v5, v6
	v_mul_lo_u32 v6, v22, v22
	v_mul_lo_u32 v7, v23, s16
	v_sub_u32_e32 v6, v7, v6
	v_or_b32_e32 v5, v5, v6
	s_nop 0
	v_readfirstlane_b32 s17, v5
	s_nop 3
	s_cmp_eq_u32 s17, 0
	s_cselect_b32 s12, 1, 2
	v_mov_b32_e32 v3, s12
	ds_write_b32 v0, v3 offset:8
	s_waitcnt lgkmcnt(0)
	s_cmp_eq_u32 s12, 1
	s_cbranch_scc0 .Lxl0_full
.Lxl0_go:
	s_and_b32 s12, s8, 15
	s_lshl_b32 s12, s12, 8
	s_add_u32 s14, s10, s12
	s_addc_u32 s15, s11, 0
	v_mov_b32_e32 v4, 0x1fa03400
	v_mov_b32_e32 v5, 1
	global_atomic_add v6, v4, v5, s[14:15] sc0
	s_waitcnt vmcnt(0)
	v_readfirstlane_b32 s16, v6
	v_cvt_f32_u32_e32 v7, s13
	v_rcp_iflag_f32_e32 v7, v7
	v_cvt_f32_u32_e32 v8, s16
	v_mul_f32_e32 v7, v8, v7
	v_cvt_u32_f32_e32 v7, v7
	s_nop 0
	v_readfirstlane_b32 s17, v7
	s_nop 3
	s_mul_i32 s12, s17, s13
	s_sub_i32 s12, s16, s12
	s_cmp_lt_i32 s12, 0
	s_cbranch_scc0 .Lxl0_f1
	s_sub_i32 s17, s17, 1
	s_add_i32 s12, s12, s13
.Lxl0_f1:
	s_cmp_ge_i32 s12, s13
	s_cbranch_scc0 .Lxl0_f2
	s_add_i32 s17, s17, 1
	s_sub_i32 s12, s12, s13
.Lxl0_f2:
	v_mov_b32_e32 v4, 0x1fa04400
	s_add_i32 s12, s12, 1
	s_cmp_eq_u32 s12, s13
	s_cbranch_scc0 .Lxl0_wait
	buffer_inv sc1
	global_atomic_add v4, v5, s[14:15]
	s_waitcnt vmcnt(0)
	s_branch .LBB0_1995
.Lxl0_wait:
	s_mov_b32 vcc_lo, 0
.Lxl0_spin:
	global_load_dword v6, v4, s[14:15] sc1
	s_waitcnt vmcnt(0)
	v_readfirstlane_b32 s16, v6
	s_nop 3
	s_cmp_eq_u32 s16, s17
	s_cbranch_scc0 .Lxl0_rel
	s_sleep 1
	s_add_i32 vcc_lo, vcc_lo, 1
	s_cmp_lt_u32 vcc_lo, 0x400000
	s_cbranch_scc1 .Lxl0_spin
.Lxl0_rel:
	buffer_inv sc1
	s_waitcnt vmcnt(0)
	s_branch .LBB0_1995
.Lxl0_full:
	v_readlane_b32 s9, v254, 32
	s_load_dwordx2 s[6:7], s[6:7], 0x80
	s_waitcnt vmcnt(0) expcnt(0) lgkmcnt(0)
	v_mov_b32_e32 v0, s9
	ds_read_b32 v2, v0
	v_readlane_b32 s9, v254, 33
	s_and_b32 s51, s8, 15
	s_waitcnt lgkmcnt(0)
	v_cmp_ne_u32_e32 vcc, 0, v2
	v_mov_b32_e32 v0, s9
	ds_read_b32 v0, v0
	s_cbranch_vccnz .LBB0_1959
	s_add_u32 s8, s6, 0x1fa02200
	s_addc_u32 s9, s7, 0
	s_add_u32 s10, s6, 0x1fa02400
	s_addc_u32 s11, s7, 0
	s_add_u32 s12, s6, 0x1fa02500
	s_addc_u32 s13, s7, 0
	s_add_u32 s14, s6, 0x1fa02600
	s_addc_u32 s15, s7, 0
	s_add_u32 s16, s6, 0x1fa02700
	s_addc_u32 s17, s7, 0
	s_add_u32 s18, s6, 0x1fa02800
	s_addc_u32 s19, s7, 0
	s_add_u32 s20, s6, 0x1fa02900
	s_addc_u32 s21, s7, 0
	s_add_u32 s22, s6, 0x1fa02a00
	s_addc_u32 s23, s7, 0
	s_add_u32 s24, s6, 0x1fa02b00
	s_addc_u32 s25, s7, 0
	s_add_u32 s26, s6, 0x1fa02c00
	s_addc_u32 s27, s7, 0
	s_add_u32 s28, s6, 0x1fa02d00
	s_addc_u32 s29, s7, 0
	s_add_u32 s30, s6, 0x1fa02e00
	s_addc_u32 s31, s7, 0
	s_add_u32 s34, s6, 0x1fa02f00
	s_addc_u32 s35, s7, 0
	s_add_u32 s36, s6, 0x1fa03000
	s_addc_u32 s37, s7, 0
	s_add_u32 s38, s6, 0x1fa03100
	s_addc_u32 s39, s7, 0
	s_add_u32 s40, s6, 0x1fa03200
	s_addc_u32 s41, s7, 0
	s_add_u32 s42, s6, 0x1fa03300
	s_addc_u32 s43, s7, 0
	s_mov_b32 s52, 1
	s_branch .LBB0_1947

; __device__ __forceinline__ unsigned xb_ld(unsigned* p)              { return __hip_atomic_load(p, __ATOMIC_RELAXED, __HIP_MEMORY_SCOPE_AGENT); }
; __device__ __forceinline__ unsigned xb_add(unsigned* p, unsigned v) { return __hip_atomic_fetch_add(p, v, __ATOMIC_RELAXED, __HIP_MEMORY_SCOPE_AGENT); }
; #define XB_SPIN(cond, bar) do { unsigned _sp = 0; while (cond) { __builtin_amdgcn_s_sleep(1); \
;     if ((++_sp & 255u) == 0u) { if (xb_ld(&(bar)[XB_TMO])) break; if (_sp > XB_SPIN_CAP) { atomicAdd(&(bar)[XB_TMO], 1u); break; } } } } while (0)
; __device__ __forceinline__ void xcd_barrier(const XcdBarrier& b, bool t0) {
;     asm volatile("s_waitcnt vmcnt(0)" ::: "memory");
;     __syncthreads();
;     if (t0) {
;         unsigned* bar = b.bar;
;         __builtin_amdgcn_s_waitcnt(0);
;         unsigned nloc = b.st[0], nx = b.st[1];
;         if (nloc == 0u) { xcd_barrier_complete(bar, b.x, nloc, nx); b.st[0] = nloc; b.st[1] = nx; }
;         const unsigned old = xb_add(&bar[XB_XSUB(b.x)], 1u);
;         const unsigned gen = old / nloc;
;         if (old + 1u == (gen + 1u) * nloc) {
;             __builtin_amdgcn_fence(__ATOMIC_RELEASE, "agent");
;             asm volatile("s_waitcnt vmcnt(0)" ::: "memory");
;             const unsigned og = xb_add(&bar[XB_TOP], 1u);
;             const unsigned tg = og / nx;
;             if (og + 1u == (tg + 1u) * nx) xb_add(&bar[XB_TOPGEN], 1u);
;             else XB_SPIN(xb_ld(&bar[XB_TOPGEN]) == tg, bar);
;             __builtin_amdgcn_fence(__ATOMIC_ACQUIRE, "agent");
;             xb_add(&bar[XB_XGEN(b.x)], 1u);
;             asm volatile("s_waitcnt vmcnt(0)" ::: "memory");
;         } else {
;             XB_SPIN(xb_ld(&bar[XB_XGEN(b.x)]) == gen, bar);
;             __builtin_amdgcn_fence(__ATOMIC_ACQUIRE, "agent");
;             asm volatile("s_waitcnt vmcnt(0)" ::: "memory");
;         }
;     }
;     __syncthreads();
; }
.LBB0_2261:
	s_mov_b64 s[6:7], s[54:55]
	s_mov_b32 s0, -1
	s_getreg_b32 s8, hwreg(HW_REG_XCC_ID, 0, 4)
	s_nop 0
	v_mbcnt_lo_u32_b32 v0, s0, 0
	v_mbcnt_hi_u32_b32 v0, s0, v0
	v_or_b32_e32 v0, s97, v0
	s_waitcnt vmcnt(0)
	s_waitcnt lgkmcnt(0)
	v_cmp_eq_u32_e32 vcc, 0, v0
	s_barrier
	s_and_saveexec_b64 s[0:1], vcc
	s_cbranch_execz .LBB0_2313
	v_readlane_b32 s9, v254, 32
	s_load_dwordx2 s[10:11], s[54:55], 0x80
	v_mov_b32_e32 v0, s9
	ds_read_b32 v2, v0
	ds_read_b32 v3, v0 offset:8
	s_waitcnt lgkmcnt(0)
	v_readfirstlane_b32 s12, v3
	v_readfirstlane_b32 s13, v2
	s_cmp_eq_u32 s12, 2
	s_cbranch_scc1 .Lxl2_full
	s_cmp_eq_u32 s13, 0
	s_cbranch_scc1 .Lxl2_full
	s_cmp_eq_u32 s12, 1
	s_cbranch_scc1 .Lxl2_go
	v_mov_b32_e32 v4, 0x1fa02000
	global_load_dwordx4 v[8:11], v4, s[10:11] sc1
	global_load_dwordx4 v[12:15], v4, s[10:11] offset:16 sc1
	global_load_dwordx4 v[16:19], v4, s[10:11] offset:32 sc1
	global_load_dwordx4 v[20:23], v4, s[10:11] offset:48 sc1
	s_lshr_b32 s16, s70, 3
	s_and_b32 s17, s70, 7
	v_mov_b32_e32 v5, s17
	s_waitcnt vmcnt(0)
	v_mul_lo_u32 v6, v8, v8
	v_mul_lo_u32 v7, v9, s16
	v_sub_u32_e32 v6, v7, v6
	v_or_b32_e32 v5, v5, v6
	v_mul_lo_u32 v6, v10, v10
	v_mul_lo_u32 v7, v11, s16
	v_sub_u32_e32 v6, v7, v6
	v_or_b32_e32 v5, v5, v6
	v_mul_lo_u32 v6, v12, v12
	v_mul_lo_u32 v7, v13, s16
	v_sub_u32_e32 v6, v7, v6
	v_or_b32_e32 v5, v5, v6
	v_mul_lo_u32 v6, v14, v14
	v_mul_lo_u32 v7, v15, s16
	v_sub_u32_e32 v6, v7, v6
	v_or_b32_e32 v5, v5, v6
	v_mul_lo_u32 v6, v16, v16
	v_mul_lo_u32 v7, v17, s16
	v_sub_u32_e32 v6, v7, v6
	v_or_b32_e32 v5, v5, v6
	v_mul_lo_u32 v6, v18, v18
	v_mul_lo_u32 v7, v19, s16
	v_sub_u32_e32 v6, v7, v6
	v_or_b32_e32 v5, v5, v6
	v_mul_lo_u32 v6, v20, v20
	v_mul_lo_u32 v7, v21, s16
	v_sub_u32_e32 v6, v7, v6
	v_or_b32_e32 v5, v5, v6
	v_mul_lo_u32 v6, v22, v22
	v_mul_lo_u32 v7, v23, s16
	v_sub_u32_e32 v6, v7, v6
	v_or_b32_e32 v5, v5, v6
	s_nop 0
	v_readfirstlane_b32 s17, v5
	s_nop 3
	s_cmp_eq_u32 s17, 0
	s_cselect_b32 s12, 1, 2
	v_mov_b32_e32 v3, s12
	ds_write_b32 v0, v3 offset:8
	s_waitcnt lgkmcnt(0)
	s_cmp_eq_u32 s12, 1
	s_cbranch_scc0 .Lxl2_full
